# pipelined attention v4: next-tile global prefetch issued before the last 8 PV MFMAs
# speedup vs baseline: 1.0054x; 1.0035x over previous
; #define MFMA32(a, b, c) __builtin_amdgcn_mfma_f32_32x32x16_bf16((a), (b), (c), 0, 0, 0)
; DI void attn_pv(const unsigned char* sV, int l31, int h, const bf16x8 (&pb)[4], f32x16 (&O)[4]) {
;     ...
;         for (int d = 0; d < 4; ++d) O[d] = MFMA32(va[d], pb[0], O[d]);
;         __builtin_amdgcn_sched_barrier(0);
; #pragma unroll
;         for (int d = 0; d < 4; ++d) va[d] = *(const bf16x8*)(vb + d * 32 * A_VROWB + 64);
;         __builtin_amdgcn_sched_barrier(0);
; #pragma unroll
;         for (int d = 0; d < 4; ++d) O[d] = MFMA32(vc[d], pb[1], O[d]);
;         __builtin_amdgcn_sched_barrier(0);
; #pragma unroll
;         for (int d = 0; d < 4; ++d) vc[d] = *(const bf16x8*)(vb + d * 32 * A_VROWB + 96);
;         __builtin_amdgcn_sched_barrier(0);
; #pragma unroll
;         for (int d = 0; d < 4; ++d) O[d] = MFMA32(va[d], pb[2], O[d]);
;         __builtin_amdgcn_sched_barrier(0);
; #pragma unroll
;         for (int d = 0; d < 4; ++d) O[d] = MFMA32(vc[d], pb[3], O[d]);
.Lpipe_nost_l:
	s_add_i32 s14, s12, 0x43
	s_cmp_ge_i32 s14, s6
	s_cbranch_scc1 .Lpipe_nopf_l
	v_add_co_u32_e32 v184, vcc, 0x10000, v144
	global_load_dwordx4 v[116:119], v[144:145], off
	s_nop 0
	v_addc_co_u32_e32 v185, vcc, 0, v145, vcc
	global_load_dwordx4 v[120:123], v[184:185], off
	global_load_dwordx4 v[124:127], v[142:143], off
	v_add_co_u32_e32 v184, vcc, 0x80000, v142
	v_lshl_add_u64 v[144:145], v[144:145], 0, s[90:91]
	s_nop 0
	v_addc_co_u32_e32 v185, vcc, 0, v143, vcc
	global_load_dwordx4 v[128:131], v[184:185], off
	v_lshl_add_u64 v[142:143], v[142:143], 0, s[88:89]
.Lpipe_nopf_l:
	s_waitcnt lgkmcnt(7)
	v_mfma_f32_32x32x16_bf16 v[50:65], v[200:203], v[224:227], v[50:65]
	s_waitcnt lgkmcnt(6)
	v_mfma_f32_32x32x16_bf16 v[34:49], v[204:207], v[224:227], v[34:49]
	s_waitcnt lgkmcnt(5)
	v_mfma_f32_32x32x16_bf16 v[18:33], v[208:211], v[224:227], v[18:33]
	s_waitcnt lgkmcnt(4)
	v_mfma_f32_32x32x16_bf16 v[2:17], v[212:215], v[224:227], v[2:17]
	s_waitcnt lgkmcnt(3)
	v_mfma_f32_32x32x16_bf16 v[50:65], v[160:163], v[228:231], v[50:65]
	s_waitcnt lgkmcnt(2)
	v_mfma_f32_32x32x16_bf16 v[34:49], v[164:167], v[228:231], v[34:49]
	s_waitcnt lgkmcnt(1)
	v_mfma_f32_32x32x16_bf16 v[18:33], v[168:171], v[228:231], v[18:33]
	s_waitcnt lgkmcnt(0)
	v_mfma_f32_32x32x16_bf16 v[2:17], v[196:199], v[228:231], v[2:17]
	s_waitcnt lgkmcnt(0)
	s_barrier
	s_branch .Lpipe_loop
